# gemm_wide (E1): hand-written compute section (saddr global loads, no address VALU, 8-slot LDS fragment pipeline across both k-steps) + half-workgroup stagger (2 barriers per k-tile, half 1 one tile ah
# baseline (speedup 1.0000x reference)
; __device__ __forceinline__ int half_id() { return __builtin_amdgcn_readfirstlane((int)(threadIdx.x >> 8)); }
; __device__ __forceinline__ int opaque_tid512() { int t = threadIdx.x; asm volatile("" : "+v"(t)); return t; }
; template <int EPI>
; __device__ __forceinline__ void gemm_wide(const WS& ws, const bf16_t* A, int lda, const bf16_t* __restrict__ W, int K, float invK,
;                                           int ntn, int ntiles, int bid) {
;     ...
;   const int tid5 = opaque_tid512(), hh = half_id();
;   const int G = gridDim.x;
;   const int nk = K >> 6;
;   if (bid < ntiles) {
;     const int my_tiles = (ntiles - 1 - bid) / G + 1;
;     const int last_id = bid + (my_tiles - 1) * G;
;     const int S = my_tiles * nk;
;     f32x4 accA[4][4], accB[4][4];
; #pragma unroll
;     for (int a = 0; a < 4; ++a)
; #pragma unroll
;       for (int b = 0; b < 4; ++b) { accA[a][b] = (f32x4){0.f, 0.f, 0.f, 0.f}; accB[a][b] = (f32x4){0.f, 0.f, 0.f, 0.f}; }
;     u32x4 ra[4], rb[4];
;     float ss[4] = {0.f, 0.f, 0.f, 0.f};
;     int l_id = bid, l_kt = 0, c_id = bid, c_kt = 0, st_kt = 0;
;     const int srow = tid >> 3;
;     const int soff = srow * 128 + (((tid & 7) ^ (srow & 7)) << 4);
;     const int wrow = tid5 >> 3;
;     const int woff = wrow * 128 + (((tid5 & 7) ^ (wrow & 7)) << 4);
;     auto issue = [&]() {
;       const int idc = l_id < last_id ? l_id : last_id;
;       int mt, nt; tile_of(idc, ntn, mt, nt);
;       const int arow = mt * 256 + hh * 128 + srow;
;       const bf16_t* akb = A + l_kt * 64 + (tid & 7) * 8;
;       const bf16_t* wp = W + (size_t)(nt * 256 + wrow) * K + l_kt * 64 + (tid5 & 7) * 8;
; #pragma unroll
;       for (int i = 0; i < 4; ++i) {
;         int r = arow + 32 * i; r = r < M_ ? r : M_ - 1;
;         ra[i] = *(const u32x4*)(akb + (size_t)r * lda);
;         rb[i] = *(const u32x4*)(wp + (size_t)i * 64 * K);
;       }
;       if (++l_kt == nk) { l_kt = 0; l_id += G; }
;     };
;     ...
;     issue();
;     store(0);
;     __syncthreads();
.LBB0_1033:
	s_and_b64 vcc, exec, s[4:5]
	s_cbranch_vccz .LBB0_574
	s_load_dwordx4 s[4:7], s[0:1], 0xc0
	s_mov_b32 s49, s93
	v_mov_b32_e32 v13, v186
	s_waitcnt vmcnt(0)
	v_mov_b32_e32 v19, v175
	s_waitcnt lgkmcnt(0)
	v_mov_b32_e32 v0, s6
	v_mov_b32_e32 v1, s7
	s_nop 0
	v_readfirstlane_b32 s58, v0
	v_readfirstlane_b32 s59, v1
	s_add_u32 s42, s58, 0x4284000
	s_addc_u32 s43, s59, 0
	s_add_u32 s44, s58, 0x62c4000
	s_addc_u32 s45, s59, 0
	s_add_u32 s46, s58, 0x8304000
	s_addc_u32 s47, s59, 0
	s_add_u32 s50, s58, 0x9324000
	s_addc_u32 s51, s59, 0
	s_add_u32 s52, s58, 0xa344000
	s_addc_u32 s53, s59, 0
	s_add_u32 s54, s58, 0xc384000
	s_addc_u32 s55, s59, 0
	s_add_u32 s56, s58, 0xe3c4000
	v_mov_b32_e32 v0, s4
	v_mov_b32_e32 v1, s5
	s_addc_u32 s57, s59, 0
	s_lshl_b64 s[4:5], s[48:49], 1
	v_readfirstlane_b32 s30, v0
	s_add_u32 s48, s30, s4
	v_writelane_b32 v240, s4, 30
	v_readfirstlane_b32 s31, v1
	s_addc_u32 s49, s31, s5
	v_writelane_b32 v240, s5, 31
	s_mov_b32 s4, s68
	s_and_b32 s5, s4, 7
	s_mul_i32 s5, s5, s75
	s_ashr_i32 s4, s4, 3
	s_add_i32 s62, s5, s4
	v_readfirstlane_b32 s4, v175
	s_cmpk_lt_i32 s62, 0x500
	s_cbranch_scc0 .LBB0_1104
	s_sub_i32 s6, 0x4ff, s62
	v_readlane_b32 s7, v240, 5
	s_mul_hi_u32 s7, s6, s7
	s_mul_i32 s8, s7, s77
	s_lshr_b32 s5, s4, 8
	s_sub_i32 s6, s6, s8
	s_lshl_b32 s4, s5, 15
	s_add_i32 s8, s7, 1
	s_sub_i32 s9, s6, s77
	s_cmp_ge_u32 s6, s77
	s_cselect_b32 s7, s8, s7
	s_cselect_b32 s6, s9, s6
	s_add_i32 s8, s7, 1
	s_cmp_ge_u32 s6, s77
	s_cselect_b32 s6, s8, s7
	s_load_dwordx2 s[8:9], s[0:1], 0x110
	s_xor_b32 s6, s6, s85
	s_sub_i32 s6, s6, s85
	v_ashrrev_i32_e32 v18, 3, v13
	s_lshl_b32 s64, s5, 7
	s_waitcnt lgkmcnt(0)
	s_mul_i32 s63, s6, s8
	s_add_i32 s63, s63, s62
	s_min_i32 s7, s62, s63
	s_mul_hi_i32 s8, s7, 0x66666667
	s_lshr_b32 s9, s8, 31
	s_ashr_i32 s8, s8, 6
	s_add_i32 s8, s8, s9
	s_mul_i32 s9, s8, 0xffffff60
	s_add_i32 s9, s9, s7
	s_lshl_b32 s7, s7, 8
	s_lshl_b32 s8, s8, 11
	s_and_b32 s7, s7, 0x700
	v_add_u32_e32 v202, s64, v18
	s_or_b32 s7, s8, s7
	v_add_u32_e32 v16, s7, v202
	v_lshlrev_b32_e32 v0, 4, v13
	s_lshl_b32 s7, s9, 5
	v_lshlrev_b32_e32 v2, 3, v19
	v_ashrrev_i32_e32 v201, 3, v19
	v_and_b32_e32 v0, 0x70, v0
	v_mov_b32_e32 v1, v12
	s_and_b32 s7, s7, 0xffffff00
	v_and_b32_e32 v2, 56, v2
	v_lshl_add_u64 v[162:163], s[58:59], 0, v[0:1]
	v_add_u32_e32 v0, s7, v201
	v_lshlrev_b32_e32 v168, 1, v2
	v_min_i32_e32 v2, 0x405f, v16
	v_ashrrev_i32_e32 v1, 31, v0
	v_ashrrev_i32_e32 v3, 31, v2
	v_lshlrev_b64 v[0:1], 11, v[0:1]
	v_lshlrev_b64 v[2:3], 11, v[2:3]
	v_lshl_add_u64 v[0:1], s[48:49], 0, v[0:1]
	v_mov_b32_e32 v169, v12
	v_lshl_add_u64 v[2:3], v[162:163], 0, v[2:3]
	v_lshl_add_u64 v[32:33], v[0:1], 0, v[168:169]
	v_min_i32_e32 v0, 0x407f, v16
	v_add_co_u32_e32 v4, vcc, s82, v2
	v_ashrrev_i32_e32 v1, 31, v0
	s_nop 0
	v_addc_co_u32_e32 v5, vcc, 0, v3, vcc
	s_mov_b32 s3, 0x20000
	v_lshlrev_b64 v[0:1], 11, v[0:1]
	v_add_co_u32_e32 v8, vcc, s3, v32
	v_lshl_add_u64 v[0:1], v[162:163], 0, v[0:1]
	s_nop 0
	v_addc_co_u32_e32 v9, vcc, 0, v33, vcc
	global_load_dwordx4 v[20:23], v[32:33], off
	s_nop 0
	global_load_dwordx4 v[0:3], v[0:1], off
	s_nop 0
	global_load_dwordx4 v[4:7], v[4:5], off
	v_xor_b32_e32 v37, v18, v13
	global_load_dwordx4 v[24:27], v[8:9], off
	v_min_i32_e32 v8, 0x403f, v16
	v_ashrrev_i32_e32 v9, 31, v8
	v_lshlrev_b64 v[8:9], 11, v[8:9]
	v_lshl_add_u64 v[8:9], v[162:163], 0, v[8:9]
	v_add_co_u32_e32 v8, vcc, s3, v8
	s_mov_b32 s3, 0x40000
	s_nop 0
	v_addc_co_u32_e32 v9, vcc, 0, v9, vcc
	v_add_co_u32_e32 v14, vcc, s3, v32
	s_mov_b32 s3, 0x30000
	s_nop 0
	v_addc_co_u32_e32 v15, vcc, 0, v33, vcc
	global_load_dwordx4 v[28:31], v[14:15], off
	v_min_i32_e32 v14, 0x401f, v16
	v_ashrrev_i32_e32 v15, 31, v14
	v_lshlrev_b64 v[14:15], 11, v[14:15]
	v_lshl_add_u64 v[14:15], v[162:163], 0, v[14:15]
	v_add_co_u32_e32 v14, vcc, s3, v14
	s_mov_b32 s3, 0x60000
	s_nop 0
	v_addc_co_u32_e32 v15, vcc, 0, v15, vcc
	v_add_co_u32_e32 v32, vcc, s3, v32
	global_load_dwordx4 v[8:11], v[8:9], off
	s_nop 0
	v_addc_co_u32_e32 v33, vcc, 0, v33, vcc
	global_load_dwordx4 v[14:17], v[14:15], off
	v_lshlrev_b32_e32 v36, 7, v18
	global_load_dwordx4 v[32:35], v[32:33], off
	v_lshlrev_b32_e32 v37, 4, v37
	s_movk_i32 s3, 0x70
	v_xor_b32_e32 v19, v201, v19
	v_and_or_b32 v36, v37, s3, v36
	v_lshlrev_b32_e32 v37, 7, v201
	v_lshlrev_b32_e32 v19, 4, v19
	v_and_or_b32 v19, v19, s3, v37
	s_lshl_b32 s34, s6, 4
	v_add_u32_e32 v203, s4, v36
	v_add_u32_e32 v204, 0x10000, v19
	s_add_i32 s34, s34, 16
	s_mov_b32 s2, 0x20000
	s_cmp_lt_i32 s34, 1
	s_waitcnt vmcnt(6)
	ds_write_b128 v203, v[0:3]
	ds_write_b128 v204, v[20:23]
	s_waitcnt vmcnt(5)
	ds_write_b128 v203, v[4:7] offset:4096
	v_add_u32_e32 v20, 0x12000, v19
	s_waitcnt vmcnt(4)
	ds_write_b128 v20, v[24:27]
	s_waitcnt vmcnt(2)
	ds_write_b128 v203, v[8:11] offset:8192
	v_add_u32_e32 v20, 0x14000, v19
	v_add_u32_e32 v19, 0x16000, v19
	ds_write_b128 v20, v[28:31]
	s_waitcnt vmcnt(1)
	ds_write_b128 v203, v[14:17] offset:12288
	s_waitcnt vmcnt(0)
	ds_write_b128 v19, v[32:35]
	s_waitcnt lgkmcnt(0)
	s_barrier
	s_cbranch_scc1 .LBB0_1104
; template <int EPI>
; __device__ __forceinline__ void gemm_wide(const WS& ws, const bf16_t* A, int lda, const bf16_t* __restrict__ W, int K, float invK,
;                                           int ntn, int ntiles, int bid) {
;     ...
;     f32x4 accA[4][4], accB[4][4];
; #pragma unroll
;     for (int a = 0; a < 4; ++a)
; #pragma unroll
;       for (int b = 0; b < 4; ++b) { accA[a][b] = (f32x4){0.f, 0.f, 0.f, 0.f}; accB[a][b] = (f32x4){0.f, 0.f, 0.f, 0.f}; }
;     u32x4 ra[4], rb[4];
;     float ss[4] = {0.f, 0.f, 0.f, 0.f};
;     int l_id = bid, l_kt = 0, c_id = bid, c_kt = 0, st_kt = 0;
;     const int srow = tid >> 3;
;     const int soff = srow * 128 + (((tid & 7) ^ (srow & 7)) << 4);
;     const int wrow = tid5 >> 3;
;     const int woff = wrow * 128 + (((tid5 & 7) ^ (wrow & 7)) << 4);
;     auto issue = [&]() {
;       const int idc = l_id < last_id ? l_id : last_id;
;       int mt, nt; tile_of(idc, ntn, mt, nt);
;       const int arow = mt * 256 + hh * 128 + srow;
;       const bf16_t* akb = A + l_kt * 64 + (tid & 7) * 8;
;       const bf16_t* wp = W + (size_t)(nt * 256 + wrow) * K + l_kt * 64 + (tid5 & 7) * 8;
; #pragma unroll
;       for (int i = 0; i < 4; ++i) {
;         int r = arow + 32 * i; r = r < M_ ? r : M_ - 1;
;         ra[i] = *(const u32x4*)(akb + (size_t)r * lda);
;         rb[i] = *(const u32x4*)(wp + (size_t)i * 64 * K);
;       }
;       if (++l_kt == nk) { l_kt = 0; l_id += G; }
;     };
;     auto store = [&](int buf) {
; #pragma unroll
;       for (int i = 0; i < 4; ++i) {
;         ss[i] += sumsq8(__builtin_bit_cast(bf16x8, ra[i]));
;         *(u32x4*)(As + buf * 16384 + i * 4096 + soff) = ra[i];
;         *(u32x4*)(Bs + buf * 32768 + i * 8192 + woff) = rb[i];
;       }
;       if (++st_kt == nk) {
;         st_kt = 0;
; #pragma unroll
;         for (int i = 0; i < 4; ++i) {
;           float t = ss[i];
;           t += __shfl_xor(t, 1); t += __shfl_xor(t, 2); t += __shfl_xor(t, 4);
;           if ((tid & 7) == 0) rsl[srow + 32 * i] = rsqrtf(t * invK + EPS_);
;           ss[i] = 0.f;
;         }
;       }
;     };
;     auto compute = [&](int buf) {
;       const unsigned char* Ab = As + buf * 16384 + (wn * 64 + lr) * 128;
;       const unsigned char* Bb = Bs + buf * 32768 + (wm * 64 + lr) * 128;
; #pragma unroll
;       for (int ks = 0; ks < 2; ++ks) {
;         if (ks == 1) __builtin_amdgcn_sched_barrier(0);
	v_and_b32_e32 v22, 0xffff0000, v14
	v_and_b32_e32 v23, 0xffff0000, v8
	v_lshlrev_b32_e32 v20, 16, v14
	v_lshlrev_b32_e32 v21, 16, v8
	v_and_b32_e32 v25, 0xffff0000, v11
	v_lshlrev_b32_e32 v27, 16, v11
	v_and_b32_e32 v29, 0xffff0000, v10
	v_and_b32_e32 v28, 0xffff0000, v16
	v_lshlrev_b32_e32 v11, 16, v10
	v_lshlrev_b32_e32 v10, 16, v16
	v_and_b32_e32 v16, 0xffff0000, v15
	v_lshlrev_b32_e32 v8, 16, v15
	v_pk_mul_f32 v[14:15], v[22:23], v[22:23]
	v_and_b32_e32 v24, 0xffff0000, v17
	v_lshlrev_b32_e32 v26, 16, v17
	v_and_b32_e32 v17, 0xffff0000, v9
	v_lshlrev_b32_e32 v9, 16, v9
	v_pk_fma_f32 v[14:15], v[20:21], v[20:21], v[14:15]
	v_and_b32_e32 v21, 0xffff0000, v2
	v_pk_fma_f32 v[8:9], v[8:9], v[8:9], v[14:15]
	v_and_b32_e32 v15, 0xffff0000, v3
	v_pk_fma_f32 v[8:9], v[16:17], v[16:17], v[8:9]
	v_lshlrev_b32_e32 v17, 16, v3
	v_pk_fma_f32 v[8:9], v[10:11], v[10:11], v[8:9]
	v_and_b32_e32 v10, 0xffff0000, v4
	v_pk_fma_f32 v[8:9], v[28:29], v[28:29], v[8:9]
	v_and_b32_e32 v11, 0xffff0000, v0
	v_pk_fma_f32 v[8:9], v[26:27], v[26:27], v[8:9]
	v_and_b32_e32 v20, 0xffff0000, v6
	v_pk_fma_f32 v[170:171], v[24:25], v[24:25], v[8:9]
	v_lshlrev_b32_e32 v8, 16, v4
	v_lshlrev_b32_e32 v9, 16, v0
	v_lshlrev_b32_e32 v3, 16, v2
	v_lshlrev_b32_e32 v2, 16, v6
	v_and_b32_e32 v6, 0xffff0000, v5
	v_lshlrev_b32_e32 v0, 16, v5
	v_pk_mul_f32 v[4:5], v[10:11], v[10:11]
	v_and_b32_e32 v14, 0xffff0000, v7
	v_lshlrev_b32_e32 v16, 16, v7
	v_and_b32_e32 v7, 0xffff0000, v1
	v_lshlrev_b32_e32 v1, 16, v1
	v_pk_fma_f32 v[4:5], v[8:9], v[8:9], v[4:5]
	v_bfe_u32 v30, v13, 6, 1
	v_pk_fma_f32 v[0:1], v[0:1], v[0:1], v[4:5]
	v_and_b32_e32 v31, 15, v13
	v_pk_fma_f32 v[0:1], v[6:7], v[6:7], v[0:1]
	v_ashrrev_i32_e32 v19, 7, v13
	v_pk_fma_f32 v[0:1], v[2:3], v[2:3], v[0:1]
	v_lshrrev_b32_e32 v32, 4, v13
	v_pk_fma_f32 v[0:1], v[20:21], v[20:21], v[0:1]
	s_lshl_b32 s5, s5, 10
	v_pk_fma_f32 v[0:1], v[16:17], v[16:17], v[0:1]
	v_bfe_u32 v33, v13, 4, 2
	v_pk_fma_f32 v[176:177], v[14:15], v[14:15], v[0:1]
	v_lshlrev_b32_e32 v0, 13, v30
	v_lshlrev_b32_e32 v1, 7, v31
	v_add3_u32 v205, s4, v0, v1
	v_lshl_or_b32 v0, v19, 13, v1
	v_add_u32_e32 v206, 0x10000, v0
	v_and_b32_e32 v0, 7, v13
	v_bitop3_b32 v1, v32, v0, 3 bitop3:0x6c
	s_add_i32 s5, s5, 0x20000
	v_lshlrev_b32_e32 v207, 4, v1
	v_bitop3_b32 v1, v33, v0, 4 bitop3:0x36
	v_lshl_or_b32 v209, v30, 6, v31
	v_lshlrev_b32_e32 v172, 6, v19
	s_movk_i32 s2, 0x80
	v_mov_b32_e32 v66, 0
	v_lshlrev_b32_e32 v208, 4, v1
	v_lshl_or_b32 v210, v209, 2, s5
	v_ashrrev_i32_e32 v173, 31, v172
	v_lshlrev_b32_e32 v174, 2, v33
	v_cmp_gt_u32_e64 s[38:39], s2, v13
	s_mov_b32 s35, 0
	v_cmp_eq_u32_e64 s[40:41], 0, v0
	v_lshl_add_u32 v211, v18, 2, s5
	s_mov_b32 s65, 1
	s_mov_b32 s6, 0
	s_mov_b32 s66, s62
	s_mov_b32 s67, 1
	v_mov_b32_e32 v67, v66
	v_mov_b32_e32 v68, v66
	v_mov_b32_e32 v69, v66
	v_mov_b32_e32 v70, v66
	v_mov_b32_e32 v71, v66
	v_mov_b32_e32 v72, v66
	v_mov_b32_e32 v73, v66
	v_mov_b32_e32 v74, v66
	v_mov_b32_e32 v75, v66
	v_mov_b32_e32 v76, v66
	v_mov_b32_e32 v77, v66
	v_mov_b32_e32 v78, v66
	v_mov_b32_e32 v79, v66
	v_mov_b32_e32 v80, v66
	v_mov_b32_e32 v81, v66
	v_mov_b32_e32 v82, v66
	v_mov_b32_e32 v83, v66
	v_mov_b32_e32 v84, v66
	v_mov_b32_e32 v85, v66
	v_mov_b32_e32 v86, v66
	v_mov_b32_e32 v87, v66
	v_mov_b32_e32 v88, v66
	v_mov_b32_e32 v89, v66
	v_mov_b32_e32 v90, v66
	v_mov_b32_e32 v91, v66
	v_mov_b32_e32 v92, v66
	v_mov_b32_e32 v93, v66
	v_mov_b32_e32 v94, v66
	v_mov_b32_e32 v95, v66
	v_mov_b32_e32 v96, v66
	v_mov_b32_e32 v97, v66
	v_mov_b32_e32 v114, v66
	v_mov_b32_e32 v115, v66
	v_mov_b32_e32 v116, v66
	v_mov_b32_e32 v117, v66
	v_mov_b32_e32 v130, v66
	v_mov_b32_e32 v131, v66
	v_mov_b32_e32 v132, v66
	v_mov_b32_e32 v133, v66
	v_mov_b32_e32 v138, v66
	v_mov_b32_e32 v139, v66
	v_mov_b32_e32 v140, v66
	v_mov_b32_e32 v141, v66
	v_mov_b32_e32 v142, v66
	v_mov_b32_e32 v143, v66
	v_mov_b32_e32 v144, v66
	v_mov_b32_e32 v145, v66
	v_mov_b32_e32 v146, v66
	v_mov_b32_e32 v147, v66
	v_mov_b32_e32 v148, v66
	v_mov_b32_e32 v149, v66
	v_mov_b32_e32 v150, v66
	v_mov_b32_e32 v151, v66
	v_mov_b32_e32 v152, v66
	v_mov_b32_e32 v153, v66
	v_mov_b32_e32 v154, v66
	v_mov_b32_e32 v155, v66
	v_mov_b32_e32 v156, v66
	v_mov_b32_e32 v157, v66
	v_mov_b32_e32 v158, v66
	v_mov_b32_e32 v159, v66
	v_mov_b32_e32 v160, v66
	v_mov_b32_e32 v161, v66
	v_mov_b32_e32 v0, v66
	v_mov_b32_e32 v1, v66
	v_mov_b32_e32 v2, v66
	v_mov_b32_e32 v3, v66
	v_mov_b32_e32 v4, v66
	v_mov_b32_e32 v5, v66
	v_mov_b32_e32 v6, v66
	v_mov_b32_e32 v7, v66
	v_mov_b32_e32 v8, v66
	v_mov_b32_e32 v9, v66
	v_mov_b32_e32 v10, v66
	v_mov_b32_e32 v11, v66
	v_mov_b32_e32 v14, v66
	v_mov_b32_e32 v15, v66
	v_mov_b32_e32 v16, v66
	v_mov_b32_e32 v17, v66
	v_mov_b32_e32 v18, v66
	v_mov_b32_e32 v19, v66
	v_mov_b32_e32 v20, v66
	v_mov_b32_e32 v21, v66
	v_mov_b32_e32 v22, v66
	v_mov_b32_e32 v23, v66
	v_mov_b32_e32 v24, v66
	v_mov_b32_e32 v25, v66
	v_mov_b32_e32 v26, v66
	v_mov_b32_e32 v27, v66
	v_mov_b32_e32 v28, v66
	v_mov_b32_e32 v29, v66
	v_mov_b32_e32 v30, v66
	v_mov_b32_e32 v31, v66
	v_mov_b32_e32 v32, v66
	v_mov_b32_e32 v33, v66
	v_mov_b32_e32 v34, v66
	v_mov_b32_e32 v35, v66
	v_mov_b32_e32 v36, v66
	v_mov_b32_e32 v37, v66
	v_mov_b32_e32 v38, v66
	v_mov_b32_e32 v39, v66
	v_mov_b32_e32 v40, v66
	v_mov_b32_e32 v41, v66
	v_mov_b32_e32 v42, v66
	v_mov_b32_e32 v43, v66
	v_mov_b32_e32 v44, v66
	v_mov_b32_e32 v45, v66
	v_mov_b32_e32 v46, v66
	v_mov_b32_e32 v47, v66
	v_mov_b32_e32 v48, v66
	v_mov_b32_e32 v49, v66
	v_mov_b32_e32 v50, v66
	v_mov_b32_e32 v51, v66
	v_mov_b32_e32 v52, v66
	v_mov_b32_e32 v53, v66
	v_mov_b32_e32 v54, v66
	v_mov_b32_e32 v55, v66
	v_mov_b32_e32 v56, v66
	v_mov_b32_e32 v57, v66
	v_mov_b32_e32 v58, v66
	v_mov_b32_e32 v59, v66
	v_mov_b32_e32 v60, v66
	v_mov_b32_e32 v61, v66
	v_mov_b32_e32 v62, v66
	v_mov_b32_e32 v63, v66
	v_mov_b32_e32 v64, v66
	v_mov_b32_e32 v65, v66
	v_subrev_u32_e32 v242, s58, v162
	v_lshl_add_u32 v242, v202, 11, v242
	v_lshl_add_u32 v243, v201, 11, v168
	s_cmp_eq_u32 s64, 0
	s_cbranch_scc1 .LBB0_1039
; template <int EPI>
; __device__ __forceinline__ void gemm_wide(const WS& ws, const bf16_t* A, int lda, const bf16_t* __restrict__ W, int K, float invK,
;                                           int ntn, int ntiles, int bid) {
;     ...
;     auto issue = [&]() {
;       const int idc = l_id < last_id ? l_id : last_id;
;       int mt, nt; tile_of(idc, ntn, mt, nt);
;       const int arow = mt * 256 + hh * 128 + srow;
;       const bf16_t* akb = A + l_kt * 64 + (tid & 7) * 8;
;       const bf16_t* wp = W + (size_t)(nt * 256 + wrow) * K + l_kt * 64 + (tid5 & 7) * 8;
; #pragma unroll
;       for (int i = 0; i < 4; ++i) {
;         int r = arow + 32 * i; r = r < M_ ? r : M_ - 1;
;         ra[i] = *(const u32x4*)(akb + (size_t)r * lda);
;         rb[i] = *(const u32x4*)(wp + (size_t)i * 64 * K);
;       }
;       if (++l_kt == nk) { l_kt = 0; l_id += G; }
;     };
	s_min_i32 s8, s66, s63
	s_mul_hi_i32 s4, s8, 0x66666667
	s_lshr_b32 s5, s4, 31
	s_ashr_i32 s4, s4, 6
	s_add_i32 s4, s4, s5
	s_mul_i32 s5, s4, 0xffffff60
	s_add_i32 s5, s5, s8
	s_ashr_i32 s7, s5, 3
	s_lshl_b32 s5, s8, 8
	s_lshl_b32 s4, s4, 11
	s_and_b32 s5, s5, 0x700
	s_or_b32 s4, s4, s5
	s_lshl_b32 s4, s4, 11
	s_lshl_b32 s7, s7, 19
	s_lshl_b32 s8, s65, 7
	s_add_u32 s4, s4, s8
	s_add_u32 s7, s7, s8
	s_add_u32 s100, s48, s7
	s_addc_u32 s101, s49, 0
	s_add_u32 s4, s58, s4
	s_addc_u32 s5, s59, 0
	global_load_dwordx4 v[126:129], v243, s[100:101]
	global_load_dwordx4 v[118:121], v242, s[4:5]
	s_add_u32 s4, s4, 0x10000
	s_addc_u32 s5, s5, 0
	global_load_dwordx4 v[106:109], v242, s[4:5]
	s_add_u32 s100, s100, 0x20000
	s_addc_u32 s101, s101, 0
	global_load_dwordx4 v[122:125], v243, s[100:101]
	s_add_u32 s4, s4, 0x10000
	s_addc_u32 s5, s5, 0
	global_load_dwordx4 v[98:101], v242, s[4:5]
	s_add_u32 s100, s100, 0x20000
	s_addc_u32 s101, s101, 0
	global_load_dwordx4 v[134:137], v243, s[100:101]
	s_add_u32 s4, s4, 0x10000
	s_addc_u32 s5, s5, 0
	global_load_dwordx4 v[102:105], v242, s[4:5]
	s_add_u32 s100, s100, 0x20000
	s_addc_u32 s101, s101, 0
	global_load_dwordx4 v[110:113], v243, s[100:101]
	s_mov_b32 s2, 0x20000
	s_mov_b32 s3, 0x60000
	s_branch .Lw_store

; template <int EPI>
; __device__ __forceinline__ void gemm_wide(const WS& ws, const bf16_t* A, int lda, const bf16_t* __restrict__ W, int K, float invK,
;                                           int ntn, int ntiles, int bid) {
;     ...
;     auto issue = [&]() {
;       const int idc = l_id < last_id ? l_id : last_id;
;       int mt, nt; tile_of(idc, ntn, mt, nt);
;       const int arow = mt * 256 + hh * 128 + srow;
;       const bf16_t* akb = A + l_kt * 64 + (tid & 7) * 8;
;       const bf16_t* wp = W + (size_t)(nt * 256 + wrow) * K + l_kt * 64 + (tid5 & 7) * 8;
; #pragma unroll
;       for (int i = 0; i < 4; ++i) {
;         int r = arow + 32 * i; r = r < M_ ? r : M_ - 1;
;         ra[i] = *(const u32x4*)(akb + (size_t)r * lda);
;         rb[i] = *(const u32x4*)(wp + (size_t)i * 64 * K);
;       }
;       if (++l_kt == nk) { l_kt = 0; l_id += G; }
;     };
;     auto store = [&](int buf) {
; #pragma unroll
;       for (int i = 0; i < 4; ++i) {
;         ss[i] += sumsq8(__builtin_bit_cast(bf16x8, ra[i]));
;         *(u32x4*)(As + buf * 16384 + i * 4096 + soff) = ra[i];
;         *(u32x4*)(Bs + buf * 32768 + i * 8192 + woff) = rb[i];
;       }
;       if (++st_kt == nk) {
;         st_kt = 0;
; #pragma unroll
;         for (int i = 0; i < 4; ++i) {
;           float t = ss[i];
;           t += __shfl_xor(t, 1); t += __shfl_xor(t, 2); t += __shfl_xor(t, 4);
;           if ((tid & 7) == 0) rsl[srow + 32 * i] = rsqrtf(t * invK + EPS_);
;           ss[i] = 0.f;
;         }
;       }
;     };
;     auto compute = [&](int buf) {
;       const unsigned char* Ab = As + buf * 16384 + (wn * 64 + lr) * 128;
;       const unsigned char* Bb = Bs + buf * 32768 + (wm * 64 + lr) * 128;
; #pragma unroll
;       for (int ks = 0; ks < 2; ++ks) {
;         if (ks == 1) __builtin_amdgcn_sched_barrier(0);
;         const int sw = ((ks * 4 + lq) ^ (lr & 7)) << 4;
;         bf16x8 xf[4], wf[4];
; #pragma unroll
;         for (int i = 0; i < 4; ++i) { xf[i] = *(const bf16x8*)(Ab + i * 2048 + sw); wf[i] = *(const bf16x8*)(Bb + i * 2048 + sw); }
; #pragma unroll
;         for (int ni = 0; ni < 4; ++ni)
; #pragma unroll
;           for (int ti = 0; ti < 4; ++ti) accA[ni][ti] = MFMA16(wf[ni], xf[ti], accA[ni][ti]);
; #pragma unroll
;         for (int i = 0; i < 4; ++i) wf[i] = *(const bf16x8*)(Bb + 16384 + i * 2048 + sw);
; #pragma unroll
;         for (int ni = 0; ni < 4; ++ni)
.LBB0_1038:
	s_load_dwordx2 s[8:9], s[0:1], 0x110
	s_add_i32 s4, s65, 1
	s_cmp_eq_u32 s4, 16
	s_cselect_b32 s65, 0, s4
	s_waitcnt lgkmcnt(0)
	s_cselect_b32 s5, s8, 0
	s_add_i32 s66, s5, s66
	s_cmp_lg_u32 s34, s35
	s_barrier
	s_cbranch_scc1 .LBB0_1039
	s_cmp_eq_u32 s64, 0
	s_cbranch_scc1 .LBB0_1104
.LBB0_1039:
	s_min_i32 s8, s66, s63
	s_mul_hi_i32 s4, s8, 0x66666667
	s_lshr_b32 s5, s4, 31
	s_ashr_i32 s4, s4, 6
	s_add_i32 s4, s4, s5
	s_mul_i32 s5, s4, 0xffffff60
	s_add_i32 s5, s5, s8
	s_ashr_i32 s7, s5, 3
	s_lshl_b32 s5, s8, 8
	s_lshl_b32 s4, s4, 11
	s_and_b32 s5, s5, 0x700
	s_or_b32 s4, s4, s5
	s_lshr_b32 s5, s64, 7
	s_add_i32 s5, s5, s35
	s_and_b32 s5, s5, 1
	v_lshl_add_u32 v13, s5, 15, v206
	v_lshl_add_u32 v226, s5, 14, v205
	v_add_u32_e32 v224, v13, v207
	v_add_u32_e32 v225, v226, v207
	ds_read_b128 v[178:181], v224
	ds_read_b128 v[182:185], v225
	ds_read_b128 v[212:215], v225 offset:2048
	ds_read_b128 v[216:219], v225 offset:4096
	ds_read_b128 v[220:223], v225 offset:6144
	ds_read_b128 v[244:247], v224 offset:2048
	ds_read_b128 v[248:251], v224 offset:4096
	ds_read_b128 v[252:255], v224 offset:6144
	v_add_u32_e32 v13, v13, v208
	v_add_u32_e32 v169, v226, v208
	s_waitcnt lgkmcnt(6)
	v_mfma_f32_16x16x32_bf16 v[158:161], v[178:181], v[182:185], v[158:161]
	s_lshl_b32 s4, s4, 11
	s_lshl_b32 s7, s7, 19
	s_lshl_b32 s8, s65, 7
	s_add_u32 s4, s4, s8
	s_add_u32 s7, s7, s8
	s_add_u32 s100, s48, s7
	s_addc_u32 s101, s49, 0
	s_add_u32 s4, s58, s4
	s_addc_u32 s5, s59, 0
	global_load_dwordx4 v[126:129], v243, s[100:101]
	s_waitcnt lgkmcnt(5)
	v_mfma_f32_16x16x32_bf16 v[154:157], v[178:181], v[212:215], v[154:157]
	s_waitcnt lgkmcnt(4)
	v_mfma_f32_16x16x32_bf16 v[150:153], v[178:181], v[216:219], v[150:153]
	s_waitcnt lgkmcnt(3)
	v_mfma_f32_16x16x32_bf16 v[146:149], v[178:181], v[220:223], v[146:149]
	ds_read_b128 v[178:181], v224 offset:16384
	s_waitcnt lgkmcnt(3)
	v_mfma_f32_16x16x32_bf16 v[142:145], v[244:247], v[182:185], v[142:145]
	global_load_dwordx4 v[118:121], v242, s[4:5]
	v_mfma_f32_16x16x32_bf16 v[138:141], v[244:247], v[212:215], v[138:141]
	v_mfma_f32_16x16x32_bf16 v[130:133], v[244:247], v[216:219], v[130:133]
	v_mfma_f32_16x16x32_bf16 v[114:117], v[244:247], v[220:223], v[114:117]
	ds_read_b128 v[244:247], v224 offset:18432
	s_waitcnt lgkmcnt(3)
	v_mfma_f32_16x16x32_bf16 v[94:97], v[248:251], v[182:185], v[94:97]
	s_add_u32 s4, s4, 0x10000
	s_addc_u32 s5, s5, 0
	global_load_dwordx4 v[106:109], v242, s[4:5]
	v_mfma_f32_16x16x32_bf16 v[90:93], v[248:251], v[212:215], v[90:93]
	v_mfma_f32_16x16x32_bf16 v[86:89], v[248:251], v[216:219], v[86:89]
	v_mfma_f32_16x16x32_bf16 v[82:85], v[248:251], v[220:223], v[82:85]
	ds_read_b128 v[248:251], v224 offset:20480
	s_waitcnt lgkmcnt(3)
	v_mfma_f32_16x16x32_bf16 v[78:81], v[252:255], v[182:185], v[78:81]
	s_add_u32 s100, s100, 0x20000
	s_addc_u32 s101, s101, 0
	global_load_dwordx4 v[122:125], v243, s[100:101]
	v_mfma_f32_16x16x32_bf16 v[74:77], v[252:255], v[212:215], v[74:77]
	v_mfma_f32_16x16x32_bf16 v[70:73], v[252:255], v[216:219], v[70:73]
	v_mfma_f32_16x16x32_bf16 v[66:69], v[252:255], v[220:223], v[66:69]
	ds_read_b128 v[252:255], v224 offset:22528
	s_waitcnt lgkmcnt(3)
	v_mfma_f32_16x16x32_bf16 v[62:65], v[178:181], v[182:185], v[62:65]
	s_add_u32 s4, s4, 0x10000
	s_addc_u32 s5, s5, 0
	global_load_dwordx4 v[98:101], v242, s[4:5]
	v_mfma_f32_16x16x32_bf16 v[58:61], v[178:181], v[212:215], v[58:61]
	v_mfma_f32_16x16x32_bf16 v[54:57], v[178:181], v[216:219], v[54:57]
	v_mfma_f32_16x16x32_bf16 v[50:53], v[178:181], v[220:223], v[50:53]
	ds_read_b128 v[178:181], v13
	s_waitcnt lgkmcnt(3)
	v_mfma_f32_16x16x32_bf16 v[46:49], v[244:247], v[182:185], v[46:49]
	s_add_u32 s100, s100, 0x20000
	s_addc_u32 s101, s101, 0
	global_load_dwordx4 v[134:137], v243, s[100:101]
	v_mfma_f32_16x16x32_bf16 v[42:45], v[244:247], v[212:215], v[42:45]
	v_mfma_f32_16x16x32_bf16 v[38:41], v[244:247], v[216:219], v[38:41]
	v_mfma_f32_16x16x32_bf16 v[34:37], v[244:247], v[220:223], v[34:37]
	ds_read_b128 v[244:247], v169
	s_waitcnt lgkmcnt(3)
; #define MFMA16(a, b, c) __builtin_amdgcn_mfma_f32_16x16x32_bf16((a), (b), (c), 0, 0, 0)
; template <int EPI>
; __device__ __forceinline__ void gemm_wide(const WS& ws, const bf16_t* A, int lda, const bf16_t* __restrict__ W, int K, float invK,
;                                           int ntn, int ntiles, int bid) {
;     ...
;       for (int ks = 0; ks < 2; ++ks) {
;         if (ks == 1) __builtin_amdgcn_sched_barrier(0);
;         const int sw = ((ks * 4 + lq) ^ (lr & 7)) << 4;
;         bf16x8 xf[4], wf[4];
; #pragma unroll
;         for (int i = 0; i < 4; ++i) { xf[i] = *(const bf16x8*)(Ab + i * 2048 + sw); wf[i] = *(const bf16x8*)(Bb + i * 2048 + sw); }
; #pragma unroll
;         for (int ni = 0; ni < 4; ++ni)
; #pragma unroll
;           for (int ti = 0; ti < 4; ++ti) accA[ni][ti] = MFMA16(wf[ni], xf[ti], accA[ni][ti]);
; #pragma unroll
;         for (int i = 0; i < 4; ++i) wf[i] = *(const bf16x8*)(Bb + 16384 + i * 2048 + sw);
; #pragma unroll
;         for (int ni = 0; ni < 4; ++ni)
; #pragma unroll
;           for (int ti = 0; ti < 4; ++ti) accB[ni][ti] = MFMA16(wf[ni], xf[ti], accB[ni][ti]);
;       }
	v_mfma_f32_16x16x32_bf16 v[30:33], v[248:251], v[182:185], v[30:33]
	s_add_u32 s4, s4, 0x10000
	s_addc_u32 s5, s5, 0
	global_load_dwordx4 v[102:105], v242, s[4:5]
	v_mfma_f32_16x16x32_bf16 v[26:29], v[248:251], v[212:215], v[26:29]
	v_mfma_f32_16x16x32_bf16 v[22:25], v[248:251], v[216:219], v[22:25]
	v_mfma_f32_16x16x32_bf16 v[18:21], v[248:251], v[220:223], v[18:21]
	ds_read_b128 v[248:251], v169 offset:2048
	s_waitcnt lgkmcnt(3)
	v_mfma_f32_16x16x32_bf16 v[14:17], v[252:255], v[182:185], v[14:17]
	s_add_u32 s100, s100, 0x20000
	s_addc_u32 s101, s101, 0
	global_load_dwordx4 v[110:113], v243, s[100:101]
	v_mfma_f32_16x16x32_bf16 v[8:11], v[252:255], v[212:215], v[8:11]
	v_mfma_f32_16x16x32_bf16 v[4:7], v[252:255], v[216:219], v[4:7]
	v_mfma_f32_16x16x32_bf16 v[0:3], v[252:255], v[220:223], v[0:3]
	ds_read_b128 v[252:255], v169 offset:4096
	ds_read_b128 v[182:185], v169 offset:6144
	ds_read_b128 v[212:215], v13 offset:2048
	ds_read_b128 v[216:219], v13 offset:4096
	ds_read_b128 v[220:223], v13 offset:6144
	s_waitcnt lgkmcnt(6)
	v_mfma_f32_16x16x32_bf16 v[158:161], v[178:181], v[244:247], v[158:161]
	s_waitcnt lgkmcnt(5)
	v_mfma_f32_16x16x32_bf16 v[154:157], v[178:181], v[248:251], v[154:157]
	s_waitcnt lgkmcnt(4)
	v_mfma_f32_16x16x32_bf16 v[150:153], v[178:181], v[252:255], v[150:153]
	s_waitcnt lgkmcnt(3)
	v_mfma_f32_16x16x32_bf16 v[146:149], v[178:181], v[182:185], v[146:149]
	ds_read_b128 v[178:181], v13 offset:16384
	s_waitcnt lgkmcnt(3)
	v_mfma_f32_16x16x32_bf16 v[142:145], v[212:215], v[244:247], v[142:145]
	v_mfma_f32_16x16x32_bf16 v[138:141], v[212:215], v[248:251], v[138:141]
	v_mfma_f32_16x16x32_bf16 v[130:133], v[212:215], v[252:255], v[130:133]
	v_mfma_f32_16x16x32_bf16 v[114:117], v[212:215], v[182:185], v[114:117]
	ds_read_b128 v[212:215], v13 offset:18432
	s_waitcnt lgkmcnt(3)
	v_mfma_f32_16x16x32_bf16 v[94:97], v[216:219], v[244:247], v[94:97]
	v_mfma_f32_16x16x32_bf16 v[90:93], v[216:219], v[248:251], v[90:93]
	v_mfma_f32_16x16x32_bf16 v[86:89], v[216:219], v[252:255], v[86:89]
	v_mfma_f32_16x16x32_bf16 v[82:85], v[216:219], v[182:185], v[82:85]
	ds_read_b128 v[216:219], v13 offset:20480
	s_waitcnt lgkmcnt(3)
	v_mfma_f32_16x16x32_bf16 v[78:81], v[220:223], v[244:247], v[78:81]
	v_mfma_f32_16x16x32_bf16 v[74:77], v[220:223], v[248:251], v[74:77]
	v_mfma_f32_16x16x32_bf16 v[70:73], v[220:223], v[252:255], v[70:73]
	v_mfma_f32_16x16x32_bf16 v[66:69], v[220:223], v[182:185], v[66:69]
	ds_read_b128 v[220:223], v13 offset:22528
	s_waitcnt lgkmcnt(3)
	v_mfma_f32_16x16x32_bf16 v[62:65], v[178:181], v[244:247], v[62:65]
	v_mfma_f32_16x16x32_bf16 v[58:61], v[178:181], v[248:251], v[58:61]
	v_mfma_f32_16x16x32_bf16 v[54:57], v[178:181], v[252:255], v[54:57]
	v_mfma_f32_16x16x32_bf16 v[50:53], v[178:181], v[182:185], v[50:53]
	s_waitcnt lgkmcnt(2)
	v_mfma_f32_16x16x32_bf16 v[46:49], v[212:215], v[244:247], v[46:49]
	v_mfma_f32_16x16x32_bf16 v[42:45], v[212:215], v[248:251], v[42:45]
	v_mfma_f32_16x16x32_bf16 v[38:41], v[212:215], v[252:255], v[38:41]
	v_mfma_f32_16x16x32_bf16 v[34:37], v[212:215], v[182:185], v[34:37]
	s_waitcnt lgkmcnt(1)
	v_mfma_f32_16x16x32_bf16 v[30:33], v[216:219], v[244:247], v[30:33]
	v_mfma_f32_16x16x32_bf16 v[26:29], v[216:219], v[248:251], v[26:29]
	v_mfma_f32_16x16x32_bf16 v[22:25], v[216:219], v[252:255], v[22:25]
	v_mfma_f32_16x16x32_bf16 v[18:21], v[216:219], v[182:185], v[18:21]
	s_waitcnt lgkmcnt(0)
	v_mfma_f32_16x16x32_bf16 v[14:17], v[220:223], v[244:247], v[14:17]
	v_mfma_f32_16x16x32_bf16 v[8:11], v[220:223], v[248:251], v[8:11]
	v_mfma_f32_16x16x32_bf16 v[4:7], v[220:223], v[252:255], v[4:7]
	v_mfma_f32_16x16x32_bf16 v[0:3], v[220:223], v[182:185], v[0:3]
	s_mov_b32 s2, 0x20000
	s_mov_b32 s3, 0x60000
	s_add_i32 s6, s6, 1
	s_cmp_lg_u32 s6, 16
	s_cbranch_scc1 .LBB0_1094
	ds_read2_b32 v[180:181], v210 offset1:16
	ds_read2_b32 v[178:179], v210 offset0:32 offset1:48
	s_cmpk_gt_i32 s62, 0x4ff
	s_mov_b64 s[4:5], -1
	s_cbranch_scc0 .LBB0_1047
	s_add_i32 s7, s62, 0xfffffb00
	s_movk_i32 s4, 0x4000
	s_cbranch_execz .LBB0_1048

; template <int EPI>
; __device__ __forceinline__ void gemm_wide(const WS& ws, const bf16_t* A, int lda, const bf16_t* __restrict__ W, int K, float invK,
;                                           int ntn, int ntiles, int bid) {
;     ...
;     for (int s = 0; s < S; ++s) {
;       issue();
;       compute(s & 1);
;       if (++c_kt == nk) { c_kt = 0; tile_end(); }
;       store((s + 1) & 1);
;       __syncthreads();
;     }
.LBB0_1094:
	s_barrier
	s_cmp_lg_u32 s34, s35
	s_cbranch_scc1 .Lw_store
	s_cmp_lg_u32 s64, 0
	s_cbranch_scc1 .LBB0_1104

; __global__ void __launch_bounds__(512, 2) fwd_megakernel(Params p) {
	.amdhsa_kernel _Z14fwd_megakernel6Params
		.amdhsa_group_segment_fixed_size 151568
		.amdhsa_private_segment_fixed_size 0
		.amdhsa_kernarg_size 528
		.amdhsa_user_sgpr_count 2
		.amdhsa_user_sgpr_dispatch_ptr 0
		.amdhsa_user_sgpr_queue_ptr 0
		.amdhsa_user_sgpr_kernarg_segment_ptr 1
		.amdhsa_user_sgpr_dispatch_id 0
		.amdhsa_user_sgpr_kernarg_preload_length 0
		.amdhsa_user_sgpr_kernarg_preload_offset 0
		.amdhsa_user_sgpr_private_segment_size 0
		.amdhsa_uses_dynamic_stack 0
		.amdhsa_enable_private_segment 0
		.amdhsa_system_sgpr_workgroup_id_x 1
		.amdhsa_system_sgpr_workgroup_id_y 0
		.amdhsa_system_sgpr_workgroup_id_z 0
		.amdhsa_system_sgpr_workgroup_info 0
		.amdhsa_system_vgpr_workitem_id 2
		.amdhsa_next_free_vgpr 256
		.amdhsa_next_free_sgpr 102
		.amdhsa_accum_offset 256
		.amdhsa_reserve_vcc 1
		.amdhsa_float_round_mode_32 0
		.amdhsa_float_round_mode_16_64 0
		.amdhsa_float_denorm_mode_32 3
		.amdhsa_float_denorm_mode_16_64 3
		.amdhsa_dx10_clamp 1
		.amdhsa_ieee_mode 1
		.amdhsa_fp16_overflow 0
		.amdhsa_tg_split 0
		.amdhsa_exception_fp_ieee_invalid_op 0
		.amdhsa_exception_fp_denorm_src 0
		.amdhsa_exception_fp_ieee_div_zero 0
		.amdhsa_exception_fp_ieee_overflow 0
		.amdhsa_exception_fp_ieee_underflow 0
		.amdhsa_exception_fp_ieee_inexact 0
		.amdhsa_exception_int_div_zero 0
	.end_amdhsa_kernel

; __global__ void __launch_bounds__(512, 2) fwd_megakernel(Params p) {
amdhsa.kernels:
  - .agpr_count:     0
    .args:
      - .offset:         0
        .size:           272
        .value_kind:     by_value
      - .offset:         272
        .size:           4
        .value_kind:     hidden_block_count_x
      - .offset:         276
        .size:           4
        .value_kind:     hidden_block_count_y
      - .offset:         280
        .size:           4
        .value_kind:     hidden_block_count_z
      - .offset:         284
        .size:           2
        .value_kind:     hidden_group_size_x
      - .offset:         286
        .size:           2
        .value_kind:     hidden_group_size_y
      - .offset:         288
        .size:           2
        .value_kind:     hidden_group_size_z
      - .offset:         290
        .size:           2
        .value_kind:     hidden_remainder_x
      - .offset:         292
        .size:           2
        .value_kind:     hidden_remainder_y
      - .offset:         294
        .size:           2
        .value_kind:     hidden_remainder_z
      - .offset:         312
        .size:           8
        .value_kind:     hidden_global_offset_x
      - .offset:         320
        .size:           8
        .value_kind:     hidden_global_offset_y
      - .offset:         328
        .size:           8
        .value_kind:     hidden_global_offset_z
      - .offset:         336
        .size:           2
        .value_kind:     hidden_grid_dims
      - .offset:         360
        .size:           8
        .value_kind:     hidden_multigrid_sync_arg
    .group_segment_fixed_size: 151568
    .kernarg_segment_align: 8
    .kernarg_segment_size: 528
    .language:       OpenCL C
    .language_version:
      - 2
      - 0
    .max_flat_workgroup_size: 512
    .name:           _Z14fwd_megakernel6Params
    .private_segment_fixed_size: 0
    .sgpr_count:     108
    .sgpr_spill_count: 96
    .symbol:         _Z14fwd_megakernel6Params.kd
    .uniform_work_group_size: 1
    .uses_dynamic_stack: false
    .vgpr_count:     256
    .vgpr_spill_count: 0
    .wavefront_size: 64
